# batched ksc scale loads in weight-convert loops (P0+P4), x->bf16 loop wait moved after load batch, pass C first wait moved
# speedup vs baseline: 1.0086x; 1.0031x over previous
.LBB0_12:
	s_or_b64 exec, exec, s[4:5]
	v_lshrrev_b32_e32 v6, 6, v4
	v_cvt_f32_ubyte0_e32 v7, v6
	v_rcp_iflag_f32_e32 v7, v7
	v_sub_u32_e32 v10, 0, v6
	v_sub_u32_e32 v9, 0, v5
	v_max_i32_e32 v9, v5, v9
	v_mul_f32_e32 v7, 0x4f7ffffe, v7
	v_cvt_u32_f32_e32 v7, v7
	v_ashrrev_i32_e32 v8, 31, v5
	v_mul_lo_u32 v10, v10, v7
	v_mul_hi_u32 v10, v7, v10
	v_add_u32_e32 v7, v7, v10
	v_mul_hi_u32 v7, v9, v7
	v_mul_lo_u32 v10, v7, v6
	v_sub_u32_e32 v9, v9, v10
	v_add_u32_e32 v11, 1, v7
	v_cmp_ge_u32_e32 vcc, v9, v6
	v_sub_u32_e32 v10, v9, v6
	s_nop 0
	v_cndmask_b32_e32 v7, v7, v11, vcc
	v_cndmask_b32_e32 v9, v9, v10, vcc
	v_add_u32_e32 v10, 1, v7
	v_cmp_ge_u32_e32 vcc, v9, v6
	s_nop 1
	v_cndmask_b32_e32 v7, v7, v10, vcc
	v_xor_b32_e32 v7, v7, v8
	v_sub_u32_e32 v7, v7, v8
	v_mul_lo_u32 v6, v7, v6
	v_sub_u32_e32 v5, v5, v6
	v_lshlrev_b32_e32 v78, 6, v5
	v_lshlrev_b32_e32 v84, 6, v7
	v_ashrrev_i32_e32 v79, 31, v78
	v_or_b32_e32 v86, v84, v70
	v_lshl_add_u64 v[2:3], v[78:79], 2, v[2:3]
	v_lshl_add_u64 v[2:3], v[2:3], 0, v[72:73]
	v_mad_i64_i32 v[6:7], s[4:5], v86, v4, 0
	v_or_b32_e32 v5, 4, v86
	v_lshl_add_u64 v[6:7], v[6:7], 2, v[2:3]
	v_mad_i64_i32 v[8:9], s[4:5], v5, v4, 0
	v_or_b32_e32 v5, 8, v86
	v_lshl_add_u64 v[8:9], v[8:9], 2, v[2:3]
	global_load_dwordx4 v[62:65], v[6:7], off nt
	global_load_dwordx4 v[58:61], v[8:9], off nt
	v_mad_i64_i32 v[6:7], s[4:5], v5, v4, 0
	v_or_b32_e32 v5, 12, v86
	v_lshl_add_u64 v[6:7], v[6:7], 2, v[2:3]
	v_mad_i64_i32 v[8:9], s[4:5], v5, v4, 0
	v_or_b32_e32 v5, 16, v86
	v_lshl_add_u64 v[8:9], v[8:9], 2, v[2:3]
	global_load_dwordx4 v[54:57], v[6:7], off nt
	global_load_dwordx4 v[50:53], v[8:9], off nt
	v_mad_i64_i32 v[6:7], s[4:5], v5, v4, 0
	v_or_b32_e32 v5, 20, v86
	v_lshl_add_u64 v[6:7], v[6:7], 2, v[2:3]
	v_mad_i64_i32 v[8:9], s[4:5], v5, v4, 0
	v_or_b32_e32 v5, 24, v86
	v_lshl_add_u64 v[8:9], v[8:9], 2, v[2:3]
	global_load_dwordx4 v[46:49], v[6:7], off nt
	global_load_dwordx4 v[42:45], v[8:9], off nt
	v_mad_i64_i32 v[6:7], s[4:5], v5, v4, 0
	v_or_b32_e32 v5, 28, v86
	v_lshl_add_u64 v[6:7], v[6:7], 2, v[2:3]
	v_mad_i64_i32 v[8:9], s[4:5], v5, v4, 0
	v_or_b32_e32 v5, 32, v86
	v_lshl_add_u64 v[8:9], v[8:9], 2, v[2:3]
	global_load_dwordx4 v[38:41], v[6:7], off nt
	global_load_dwordx4 v[34:37], v[8:9], off nt
	v_mad_i64_i32 v[6:7], s[4:5], v5, v4, 0
	v_or_b32_e32 v5, 36, v86
	v_lshl_add_u64 v[6:7], v[6:7], 2, v[2:3]
	v_mad_i64_i32 v[8:9], s[4:5], v5, v4, 0
	v_or_b32_e32 v5, 40, v86
	v_lshl_add_u64 v[8:9], v[8:9], 2, v[2:3]
	global_load_dwordx4 v[30:33], v[6:7], off nt
	global_load_dwordx4 v[26:29], v[8:9], off nt
	v_mad_i64_i32 v[6:7], s[4:5], v5, v4, 0
	v_or_b32_e32 v5, 44, v86
	v_lshl_add_u64 v[6:7], v[6:7], 2, v[2:3]
	v_mad_i64_i32 v[8:9], s[4:5], v5, v4, 0
	v_or_b32_e32 v5, 48, v86
	v_lshl_add_u64 v[8:9], v[8:9], 2, v[2:3]
	global_load_dwordx4 v[22:25], v[6:7], off nt
	global_load_dwordx4 v[18:21], v[8:9], off nt
	v_mad_i64_i32 v[6:7], s[4:5], v5, v4, 0
	v_or_b32_e32 v5, 52, v86
	v_lshl_add_u64 v[6:7], v[6:7], 2, v[2:3]
	v_mad_i64_i32 v[8:9], s[4:5], v5, v4, 0
	v_or_b32_e32 v5, 56, v86
	v_lshl_add_u64 v[8:9], v[8:9], 2, v[2:3]
	global_load_dwordx4 v[14:17], v[6:7], off nt
	global_load_dwordx4 v[10:13], v[8:9], off nt
	v_mad_i64_i32 v[6:7], s[4:5], v5, v4, 0
	v_or_b32_e32 v5, 60, v86
	v_mad_i64_i32 v[4:5], s[4:5], v5, v4, 0
	v_lshl_add_u64 v[6:7], v[6:7], 2, v[2:3]
	v_lshl_add_u64 v[2:3], v[4:5], 2, v[2:3]
	global_load_dwordx4 v[6:9], v[6:7], off nt
	s_nop 0
	global_load_dwordx4 v[2:5], v[2:3], off nt
	v_cmp_ne_u64_e32 vcc, 0, v[82:83]
	v_ashrrev_i32_e32 v85, 31, v84
	s_and_saveexec_b64 s[4:5], vcc
	s_xor_b64 s[4:5], exec, s[4:5]
	s_cbranch_execz .LBB0_14
	v_ashrrev_i32_e32 v87, 31, v86
	v_lshl_add_u64 v[86:87], v[86:87], 2, v[82:83]
	v_lshl_add_u64 v[104:105], v[84:85], 0, v[70:71]
	global_load_dword v86, v[86:87], off
	v_lshl_add_u64 v[104:105], v[104:105], 2, v[82:83]
	global_load_dword v88, v[104:105], off offset:16
	global_load_dword v120, v[104:105], off offset:32
	global_load_dword v121, v[104:105], off offset:48
	global_load_dword v122, v[104:105], off offset:64
	global_load_dword v123, v[104:105], off offset:80
	global_load_dword v124, v[104:105], off offset:96
	global_load_dword v125, v[104:105], off offset:112
	global_load_dword v126, v[104:105], off offset:128
	global_load_dword v127, v[104:105], off offset:144
	global_load_dword v128, v[104:105], off offset:160
	global_load_dword v129, v[104:105], off offset:176
	global_load_dword v130, v[104:105], off offset:192
	global_load_dword v131, v[104:105], off offset:208
	global_load_dword v132, v[104:105], off offset:224
	global_load_dword v133, v[104:105], off offset:240
	s_waitcnt vmcnt(15)
	v_pk_mul_f32 v[62:63], v[62:63], v[86:87] op_sel_hi:[1,0]
	v_pk_mul_f32 v[64:65], v[64:65], v[86:87] op_sel_hi:[1,0]
	ds_write2_b32 v99, v62, v63 offset1:1
	ds_write2_b32 v99, v64, v65 offset0:2 offset1:3

.LBB0_16:
	s_or_b64 exec, exec, s[4:5]
	s_waitcnt vmcnt(0)
	v_pk_mul_f32 v[58:59], v[58:59], v[88:89] op_sel_hi:[1,0]
	ds_write2_b32 v97, v58, v59 offset1:1
	v_pk_mul_f32 v[58:59], v[60:61], v[88:89] op_sel_hi:[1,0]
	ds_write2_b32 v97, v58, v59 offset0:2 offset1:3
	s_and_saveexec_b64 s[4:5], vcc
	s_xor_b64 s[4:5], exec, s[4:5]
	s_cbranch_execz .LBB0_18
	v_lshl_add_u64 v[58:59], v[84:85], 0, v[70:71]
	v_lshl_add_u64 v[58:59], v[58:59], 2, v[82:83]
	v_mov_b32_e32 v60, v120
	s_nop 0
	v_mov_b32_e32 v58, v121
	s_waitcnt vmcnt(1)
	v_pk_mul_f32 v[54:55], v[54:55], v[60:61] op_sel_hi:[1,0]
	v_pk_mul_f32 v[56:57], v[56:57], v[60:61] op_sel_hi:[1,0]
	ds_write2_b32 v100, v54, v55 offset1:1
	ds_write2_b32 v100, v56, v57 offset0:2 offset1:3

.LBB0_20:
	s_or_b64 exec, exec, s[4:5]
	s_waitcnt vmcnt(0)
	v_pk_mul_f32 v[50:51], v[50:51], v[58:59] op_sel_hi:[1,0]
	ds_write2_b32 v98, v50, v51 offset1:1
	v_pk_mul_f32 v[50:51], v[52:53], v[58:59] op_sel_hi:[1,0]
	ds_write2_b32 v98, v50, v51 offset0:2 offset1:3
	s_and_saveexec_b64 s[4:5], vcc
	s_xor_b64 s[4:5], exec, s[4:5]
	s_cbranch_execz .LBB0_22
	v_lshl_add_u64 v[50:51], v[84:85], 0, v[70:71]
	v_lshl_add_u64 v[50:51], v[50:51], 2, v[82:83]
	v_mov_b32_e32 v52, v122
	s_nop 0
	v_mov_b32_e32 v50, v123
	s_waitcnt vmcnt(1)
	v_pk_mul_f32 v[46:47], v[46:47], v[52:53] op_sel_hi:[1,0]
	v_pk_mul_f32 v[48:49], v[48:49], v[52:53] op_sel_hi:[1,0]
	ds_write2_b32 v101, v46, v47 offset1:1
	ds_write2_b32 v101, v48, v49 offset0:2 offset1:3

.LBB0_24:
	s_or_b64 exec, exec, s[4:5]
	s_waitcnt vmcnt(0)
	v_pk_mul_f32 v[42:43], v[42:43], v[50:51] op_sel_hi:[1,0]
	v_add_u32_e32 v46, 0x410, v101
	ds_write2_b32 v46, v42, v43 offset1:1
	v_pk_mul_f32 v[42:43], v[44:45], v[50:51] op_sel_hi:[1,0]
	v_add_u32_e32 v44, 0x418, v101
	ds_write2_b32 v44, v42, v43 offset1:1
	v_add_u32_e32 v43, 0x820, v101
	v_add_u32_e32 v44, 0x828, v101
	s_and_saveexec_b64 s[4:5], vcc
	s_xor_b64 s[4:5], exec, s[4:5]
	s_cbranch_execz .LBB0_26
	v_lshl_add_u64 v[46:47], v[84:85], 0, v[70:71]
	v_lshl_add_u64 v[46:47], v[46:47], 2, v[82:83]
	v_mov_b32_e32 v48, v124
	v_mov_b32_e32 v42, v125
	s_waitcnt vmcnt(1)
	v_pk_mul_f32 v[38:39], v[38:39], v[48:49] op_sel_hi:[1,0]
	v_pk_mul_f32 v[40:41], v[40:41], v[48:49] op_sel_hi:[1,0]
	ds_write2_b32 v43, v38, v39 offset1:1
	ds_write2_b32 v44, v40, v41 offset1:1

.LBB0_28:
	s_or_b64 exec, exec, s[4:5]
	s_waitcnt vmcnt(0)
	v_pk_mul_f32 v[34:35], v[34:35], v[42:43] op_sel_hi:[1,0]
	v_add_u32_e32 v38, 0xc30, v101
	ds_write2_b32 v38, v34, v35 offset1:1
	v_pk_mul_f32 v[34:35], v[36:37], v[42:43] op_sel_hi:[1,0]
	v_add_u32_e32 v36, 0xc38, v101
	ds_write2_b32 v36, v34, v35 offset1:1
	v_add_u32_e32 v35, 0x1040, v101
	v_add_u32_e32 v36, 0x1048, v101
	s_and_saveexec_b64 s[4:5], vcc
	s_xor_b64 s[4:5], exec, s[4:5]
	s_cbranch_execz .LBB0_30
	v_lshl_add_u64 v[38:39], v[84:85], 0, v[70:71]
	v_lshl_add_u64 v[38:39], v[38:39], 2, v[82:83]
	v_mov_b32_e32 v40, v126
	v_mov_b32_e32 v34, v127
	s_waitcnt vmcnt(1)
	v_pk_mul_f32 v[30:31], v[30:31], v[40:41] op_sel_hi:[1,0]
	v_pk_mul_f32 v[32:33], v[32:33], v[40:41] op_sel_hi:[1,0]
	ds_write2_b32 v35, v30, v31 offset1:1
	ds_write2_b32 v36, v32, v33 offset1:1

.LBB0_32:
	s_or_b64 exec, exec, s[4:5]
	s_waitcnt vmcnt(0)
	v_pk_mul_f32 v[26:27], v[26:27], v[34:35] op_sel_hi:[1,0]
	v_add_u32_e32 v30, 0x1450, v101
	ds_write2_b32 v30, v26, v27 offset1:1
	v_pk_mul_f32 v[26:27], v[28:29], v[34:35] op_sel_hi:[1,0]
	v_add_u32_e32 v28, 0x1458, v101
	ds_write2_b32 v28, v26, v27 offset1:1
	v_add_u32_e32 v27, 0x1860, v101
	v_add_u32_e32 v28, 0x1868, v101
	s_and_saveexec_b64 s[4:5], vcc
	s_xor_b64 s[4:5], exec, s[4:5]
	s_cbranch_execz .LBB0_34
	v_lshl_add_u64 v[30:31], v[84:85], 0, v[70:71]
	v_lshl_add_u64 v[30:31], v[30:31], 2, v[82:83]
	v_mov_b32_e32 v32, v128
	v_mov_b32_e32 v26, v129
	s_waitcnt vmcnt(1)
	v_pk_mul_f32 v[22:23], v[22:23], v[32:33] op_sel_hi:[1,0]
	v_pk_mul_f32 v[24:25], v[24:25], v[32:33] op_sel_hi:[1,0]
	ds_write2_b32 v27, v22, v23 offset1:1
	ds_write2_b32 v28, v24, v25 offset1:1

.LBB0_36:
	s_or_b64 exec, exec, s[4:5]
	s_waitcnt vmcnt(0)
	v_pk_mul_f32 v[18:19], v[18:19], v[26:27] op_sel_hi:[1,0]
	v_add_u32_e32 v22, 0x1c70, v101
	ds_write2_b32 v22, v18, v19 offset1:1
	v_pk_mul_f32 v[18:19], v[20:21], v[26:27] op_sel_hi:[1,0]
	v_add_u32_e32 v20, 0x1c78, v101
	ds_write2_b32 v20, v18, v19 offset1:1
	v_add_u32_e32 v19, 0x2080, v101
	v_add_u32_e32 v20, 0x2088, v101
	s_and_saveexec_b64 s[4:5], vcc
	s_xor_b64 s[4:5], exec, s[4:5]
	s_cbranch_execz .LBB0_38
	v_lshl_add_u64 v[22:23], v[84:85], 0, v[70:71]
	v_lshl_add_u64 v[22:23], v[22:23], 2, v[82:83]
	v_mov_b32_e32 v24, v130
	v_mov_b32_e32 v18, v131
	s_waitcnt vmcnt(1)
	v_pk_mul_f32 v[14:15], v[14:15], v[24:25] op_sel_hi:[1,0]
	v_pk_mul_f32 v[16:17], v[16:17], v[24:25] op_sel_hi:[1,0]
	ds_write2_b32 v19, v14, v15 offset1:1
	ds_write2_b32 v20, v16, v17 offset1:1

.LBB0_40:
	s_or_b64 exec, exec, s[4:5]
	s_waitcnt vmcnt(0)
	v_pk_mul_f32 v[10:11], v[10:11], v[18:19] op_sel_hi:[1,0]
	v_add_u32_e32 v14, 0x2490, v101
	ds_write2_b32 v14, v10, v11 offset1:1
	v_pk_mul_f32 v[10:11], v[12:13], v[18:19] op_sel_hi:[1,0]
	v_add_u32_e32 v12, 0x2498, v101
	ds_write2_b32 v12, v10, v11 offset1:1
	v_add_u32_e32 v11, 0x28a0, v101
	v_add_u32_e32 v12, 0x28a8, v101
	s_and_saveexec_b64 s[4:5], vcc
	s_xor_b64 s[4:5], exec, s[4:5]
	s_cbranch_execz .LBB0_42
	v_lshl_add_u64 v[14:15], v[84:85], 0, v[70:71]
	v_lshl_add_u64 v[14:15], v[14:15], 2, v[82:83]
	v_mov_b32_e32 v16, v132
	v_mov_b32_e32 v10, v133
	s_waitcnt vmcnt(1)
	v_pk_mul_f32 v[6:7], v[6:7], v[16:17] op_sel_hi:[1,0]
	v_pk_mul_f32 v[8:9], v[8:9], v[16:17] op_sel_hi:[1,0]
	ds_write2_b32 v11, v6, v7 offset1:1
	ds_write2_b32 v12, v8, v9 offset1:1

.LBB0_72:
	v_add_u32_e32 v68, s85, v66
	v_ashrrev_i32_e32 v67, 31, v66
	v_cmp_gt_i32_e64 s[2:3], s10, v68
	v_lshlrev_b64 v[2:3], 13, v[66:67]
	v_lshl_add_u64 v[2:3], v[52:53], 0, v[2:3]
	v_cndmask_b32_e64 v56, v66, v68, s[2:3]
	v_ashrrev_i32_e32 v57, 31, v56
	global_load_dwordx4 v[70:73], v[2:3], off nt
	global_load_dwordx4 v[46:49], v[2:3], off offset:1024 nt
	global_load_dwordx4 v[38:41], v[2:3], off offset:2048 nt
	global_load_dwordx4 v[26:29], v[2:3], off offset:3072 nt
	v_add_co_u32_e64 v2, s[2:3], s11, v2
	v_lshlrev_b64 v[4:5], 13, v[56:57]
	s_nop 0
	v_addc_co_u32_e64 v3, s[2:3], 0, v3, s[2:3]
	v_lshl_add_u64 v[4:5], v[52:53], 0, v[4:5]
	global_load_dwordx4 v[22:25], v[2:3], off nt
	global_load_dwordx4 v[74:77], v[4:5], off nt
	global_load_dwordx4 v[78:81], v[4:5], off offset:1024 nt
	global_load_dwordx4 v[82:85], v[4:5], off offset:2048 nt
	global_load_dwordx4 v[42:45], v[4:5], off offset:3072 nt
	v_add_co_u32_e64 v4, s[2:3], s11, v4
	s_waitcnt lgkmcnt(1)
	s_nop 0
	v_addc_co_u32_e64 v5, s[2:3], 0, v5, s[2:3]
	global_load_dwordx4 v[34:37], v[4:5], off nt
	global_load_dwordx4 v[18:21], v[4:5], off offset:1024 nt
	global_load_dwordx4 v[30:33], v[2:3], off offset:1024 nt
	global_load_dwordx4 v[10:13], v[4:5], off offset:2048 nt
	global_load_dwordx4 v[14:17], v[2:3], off offset:2048 nt
	global_load_dwordx4 v[6:9], v[2:3], off offset:3072 nt
	s_nop 0
	global_load_dwordx4 v[2:5], v[4:5], off offset:3072 nt
	s_waitcnt vmcnt(14)
	v_mov_b32_e32 v61, v71
	v_mov_b32_e32 v93, v47
	v_mov_b32_e32 v59, v70
	v_mov_b32_e32 v91, v46
	s_waitcnt vmcnt(13)
	v_mov_b32_e32 v101, v39
	s_waitcnt vmcnt(10) lgkmcnt(0)
	v_mov_b32_e32 v60, v75
	s_waitcnt vmcnt(9)
	v_mov_b32_e32 v92, v79
	v_mov_b32_e32 v58, v74
	v_mov_b32_e32 v90, v78
	s_waitcnt vmcnt(8)
	v_mov_b32_e32 v100, v83
	v_pk_mul_f32 v[60:61], v[60:61], v[60:61]
	v_pk_mul_f32 v[92:93], v[92:93], v[92:93]
	v_mov_b32_e32 v87, v72
	v_mov_b32_e32 v95, v48
	v_mov_b32_e32 v99, v38
	v_mov_b32_e32 v109, v27
	v_mov_b32_e32 v86, v76
	v_mov_b32_e32 v94, v80
	v_mov_b32_e32 v98, v82
	s_waitcnt vmcnt(7)
	v_mov_b32_e32 v108, v43
	v_pk_mul_f32 v[100:101], v[100:101], v[100:101]
	v_pk_fma_f32 v[58:59], v[58:59], v[58:59], v[60:61]
	v_pk_fma_f32 v[60:61], v[90:91], v[90:91], v[92:93]
	v_mov_b32_e32 v89, v73
	v_mov_b32_e32 v97, v49
	v_mov_b32_e32 v103, v40
	v_mov_b32_e32 v107, v26
	v_mov_b32_e32 v117, v23
	v_mov_b32_e32 v88, v77
	v_mov_b32_e32 v96, v81
	v_mov_b32_e32 v102, v84
	v_mov_b32_e32 v106, v42
	v_pk_mul_f32 v[108:109], v[108:109], v[108:109]
	v_pk_fma_f32 v[90:91], v[98:99], v[98:99], v[100:101]
	v_pk_fma_f32 v[58:59], v[86:87], v[86:87], v[58:59]
	v_pk_fma_f32 v[60:61], v[94:95], v[94:95], v[60:61]
	v_mov_b32_e32 v105, v41
	v_mov_b32_e32 v111, v28
	v_mov_b32_e32 v115, v22
	v_mov_b32_e32 v104, v85
	v_mov_b32_e32 v110, v44
	v_pk_fma_f32 v[92:93], v[106:107], v[106:107], v[108:109]
	v_pk_fma_f32 v[86:87], v[102:103], v[102:103], v[90:91]
	v_pk_fma_f32 v[58:59], v[88:89], v[88:89], v[58:59]
	v_pk_fma_f32 v[60:61], v[96:97], v[96:97], v[60:61]
	v_mov_b32_e32 v113, v29
	v_mov_b32_e32 v119, v24
	v_mov_b32_e32 v112, v45
	v_pk_fma_f32 v[90:91], v[110:111], v[110:111], v[92:93]
	v_pk_fma_f32 v[86:87], v[104:105], v[104:105], v[86:87]
	v_pk_add_f32 v[58:59], v[58:59], v[60:61]
	v_pk_fma_f32 v[88:89], v[112:113], v[112:113], v[90:91]
	v_pk_add_f32 v[58:59], v[58:59], v[86:87]
	v_mov_b32_e32 v61, v25
	v_pk_add_f32 v[58:59], v[58:59], v[88:89]
	v_cvt_pk_bf16_f32 v22, v22, v23
	v_cvt_pk_bf16_f32 v23, v24, v25
	v_cvt_pk_bf16_f32 v70, v70, v71
	v_cvt_pk_bf16_f32 v71, v72, v73
	v_cvt_pk_bf16_f32 v46, v46, v47
	v_cvt_pk_bf16_f32 v47, v48, v49
	v_cvt_pk_bf16_f32 v38, v38, v39
	v_cvt_pk_bf16_f32 v39, v40, v41
	v_cvt_pk_bf16_f32 v26, v26, v27
	v_cvt_pk_bf16_f32 v27, v28, v29
	s_waitcnt vmcnt(6)
	v_mov_b32_e32 v116, v35
	v_mov_b32_e32 v114, v34
	v_pk_mul_f32 v[98:99], v[116:117], v[116:117]
	v_mov_b32_e32 v118, v36
	v_pk_fma_f32 v[92:93], v[114:115], v[114:115], v[98:99]
	v_mov_b32_e32 v60, v37
	v_pk_fma_f32 v[90:91], v[118:119], v[118:119], v[92:93]
	s_waitcnt vmcnt(5)
	v_mov_b32_e32 v86, v19
	v_pk_fma_f32 v[60:61], v[60:61], v[60:61], v[90:91]
	s_waitcnt vmcnt(4)
	v_mov_b32_e32 v87, v31
	v_pk_add_f32 v[58:59], v[58:59], v[60:61]
	v_mov_b32_e32 v60, v18
	v_mov_b32_e32 v61, v30
	v_pk_mul_f32 v[86:87], v[86:87], v[86:87]
	s_waitcnt vmcnt(3)
	v_mov_b32_e32 v88, v11
	v_pk_fma_f32 v[60:61], v[60:61], v[60:61], v[86:87]
	v_mov_b32_e32 v86, v20
	v_mov_b32_e32 v87, v32
	v_pk_fma_f32 v[60:61], v[86:87], v[86:87], v[60:61]
	v_mov_b32_e32 v86, v21
	v_mov_b32_e32 v87, v33
	s_waitcnt vmcnt(2)
	v_mov_b32_e32 v89, v15
	v_pk_fma_f32 v[60:61], v[86:87], v[86:87], v[60:61]
	v_mov_b32_e32 v86, v10
	v_mov_b32_e32 v87, v14
	v_pk_mul_f32 v[88:89], v[88:89], v[88:89]
	s_waitcnt vmcnt(0)
	v_mov_b32_e32 v92, v3
	v_pk_fma_f32 v[86:87], v[86:87], v[86:87], v[88:89]
	v_mov_b32_e32 v88, v12
	v_mov_b32_e32 v89, v16
	v_mov_b32_e32 v93, v7
	v_pk_fma_f32 v[86:87], v[88:89], v[88:89], v[86:87]
	v_mov_b32_e32 v88, v13
	v_mov_b32_e32 v89, v17
	v_mov_b32_e32 v90, v2
	v_mov_b32_e32 v91, v6
	v_pk_mul_f32 v[92:93], v[92:93], v[92:93]
	v_pk_add_f32 v[58:59], v[58:59], v[60:61]
	v_pk_fma_f32 v[90:91], v[90:91], v[90:91], v[92:93]
	v_mov_b32_e32 v92, v4
	v_mov_b32_e32 v93, v8
	v_pk_fma_f32 v[60:61], v[88:89], v[88:89], v[86:87]
	v_mov_b32_e32 v86, v5
	v_pk_add_f32 v[58:59], v[58:59], v[60:61]
	v_pk_fma_f32 v[60:61], v[92:93], v[92:93], v[90:91]
	v_mov_b32_e32 v87, v9
	v_pk_fma_f32 v[60:61], v[86:87], v[86:87], v[60:61]
	v_lshlrev_b64 v[86:87], 12, v[66:67]
	v_pk_add_f32 v[58:59], v[58:59], v[60:61]
	ds_bpermute_b32 v61, v1, v59
	ds_bpermute_b32 v60, v1, v58
	v_lshl_add_u64 v[86:87], v[50:51], 0, v[86:87]
	v_lshlrev_b64 v[88:89], 12, v[56:57]
	v_lshl_add_u64 v[88:89], v[50:51], 0, v[88:89]
	global_store_dwordx2 v[86:87], v[22:23], off offset:2048
	s_waitcnt lgkmcnt(0)
	v_pk_add_f32 v[58:59], v[58:59], v[60:61]
	ds_bpermute_b32 v61, v55, v59
	ds_bpermute_b32 v60, v55, v58
	v_cvt_pk_bf16_f32 v22, v34, v35
	v_cvt_pk_bf16_f32 v23, v36, v37
	global_store_dwordx2 v[86:87], v[70:71], off
	v_cvt_pk_bf16_f32 v70, v74, v75
	s_waitcnt lgkmcnt(0)
	v_pk_add_f32 v[58:59], v[58:59], v[60:61]
	ds_bpermute_b32 v61, v62, v59
	ds_bpermute_b32 v60, v62, v58
	v_cvt_pk_bf16_f32 v71, v76, v77
	global_store_dwordx2 v[86:87], v[46:47], off offset:512
	v_cvt_pk_bf16_f32 v46, v78, v79
	v_cvt_pk_bf16_f32 v47, v80, v81
	s_waitcnt lgkmcnt(0)
	v_pk_add_f32 v[58:59], v[58:59], v[60:61]
	ds_bpermute_b32 v61, v63, v59
	ds_bpermute_b32 v60, v63, v58
	global_store_dwordx2 v[86:87], v[38:39], off offset:1024
	v_cvt_pk_bf16_f32 v38, v82, v83
	v_cvt_pk_bf16_f32 v39, v84, v85
	global_store_dwordx2 v[86:87], v[26:27], off offset:1536
	s_waitcnt lgkmcnt(0)
	v_pk_add_f32 v[58:59], v[58:59], v[60:61]
	ds_bpermute_b32 v61, v64, v59
	ds_bpermute_b32 v60, v64, v58
	v_cvt_pk_bf16_f32 v26, v42, v43
	v_cvt_pk_bf16_f32 v27, v44, v45
	global_store_dwordx2 v[88:89], v[22:23], off offset:2048
	v_cvt_pk_bf16_f32 v22, v30, v31
	s_waitcnt lgkmcnt(0)
	v_pk_add_f32 v[58:59], v[58:59], v[60:61]
	ds_bpermute_b32 v61, v65, v59
	ds_bpermute_b32 v60, v65, v58
	v_cvt_pk_bf16_f32 v23, v32, v33
	v_cvt_pk_bf16_f32 v18, v18, v19
	v_cvt_pk_bf16_f32 v19, v20, v21
	v_cvt_pk_bf16_f32 v14, v14, v15
	v_cvt_pk_bf16_f32 v15, v16, v17
	v_cvt_pk_bf16_f32 v10, v10, v11
	v_cvt_pk_bf16_f32 v11, v12, v13
	v_cvt_pk_bf16_f32 v6, v6, v7
	v_cvt_pk_bf16_f32 v7, v8, v9
	v_cvt_pk_bf16_f32 v2, v2, v3
	v_cvt_pk_bf16_f32 v3, v4, v5
	global_store_dwordx2 v[88:89], v[70:71], off
	global_store_dwordx2 v[88:89], v[46:47], off offset:512
	global_store_dwordx2 v[88:89], v[38:39], off offset:1024
	global_store_dwordx2 v[88:89], v[26:27], off offset:1536
	global_store_dwordx2 v[86:87], v[22:23], off offset:2560
	global_store_dwordx2 v[88:89], v[18:19], off offset:2560
	global_store_dwordx2 v[86:87], v[14:15], off offset:3072
	global_store_dwordx2 v[88:89], v[10:11], off offset:3072
	global_store_dwordx2 v[86:87], v[6:7], off offset:3584
	global_store_dwordx2 v[88:89], v[2:3], off offset:3584
	s_and_saveexec_b64 s[8:9], vcc
	s_cbranch_execz .LBB0_71
	s_waitcnt lgkmcnt(0)
	v_pk_add_f32 v[4:5], v[58:59], v[60:61]
	v_lshl_add_u64 v[2:3], v[66:67], 2, s[92:93]
	v_pk_fma_f32 v[4:5], v[4:5], s[14:15], v[54:55] op_sel_hi:[1,0,0]
	s_nop 0
	v_mul_f32_e32 v6, 0x4b800000, v5
	v_cmp_gt_f32_e64 s[2:3], s15, v5
	v_cmp_gt_f32_e64 s[4:5], s15, v4
	s_nop 0
	v_cndmask_b32_e64 v5, v5, v6, s[2:3]
	v_rsq_f32_e32 v5, v5
	v_mul_f32_e32 v6, 0x4b800000, v4
	v_cndmask_b32_e64 v4, v4, v6, s[4:5]
	v_rsq_f32_e32 v4, v4
	v_mul_f32_e32 v6, 0x45800000, v5
	v_cndmask_b32_e64 v5, v5, v6, s[2:3]
	global_store_dword v[2:3], v5, off
	v_mul_f32_e32 v2, 0x45800000, v4
	v_cndmask_b32_e64 v4, v4, v2, s[4:5]
	v_lshl_add_u64 v[2:3], v[56:57], 2, s[92:93]
	global_store_dword v[2:3], v4, off
	s_branch .LBB0_71

.LBB0_644:
	s_mul_i32 s6, s59, 0x51000
	s_add_i32 s7, s6, s17
	buffer_load_dwordx4 v[66:69], v206, s[12:15], s7 offen nt
	v_readlane_b32 s7, v245, 32
	s_andn2_b64 vcc, exec, s[68:69]
	s_nop 3
	buffer_load_dwordx4 v[2:5], v206, s[12:15], s7 offen nt
	v_readlane_b32 s7, v245, 40
	s_add_i32 s7, s7, s6
	s_nop 1
	s_nop 1
	buffer_load_dwordx4 v[70:73], v206, s[12:15], s7 offen nt
	v_readlane_b32 s7, v245, 41
	s_nop 0
	s_nop 3
	buffer_load_dwordx4 v[62:65], v206, s[12:15], s7 offen nt
	s_add_i32 s7, s26, s6
	buffer_load_dwordx4 v[74:77], v206, s[12:15], s7 offen nt
	buffer_load_dwordx4 v[134:137], v206, s[12:15], s27 offen nt
	s_add_i32 s7, s33, s6
	buffer_load_dwordx4 v[78:81], v206, s[12:15], s7 offen nt
	buffer_load_dwordx4 v[138:141], v206, s[12:15], s31 offen nt
	s_add_i32 s7, s20, s6
	buffer_load_dwordx4 v[82:85], v206, s[12:15], s7 offen nt
	buffer_load_dwordx4 v[162:165], v206, s[12:15], s28 offen nt
	s_add_i32 s7, s29, s6
	buffer_load_dwordx4 v[86:89], v206, s[12:15], s7 offen nt
	buffer_load_dwordx4 v[166:169], v206, s[12:15], s30 offen nt
	s_add_i32 s7, s21, s6
	s_add_i32 s6, s65, s6
	buffer_load_dwordx4 v[90:93], v206, s[12:15], s7 offen nt
	buffer_load_dwordx4 v[170:173], v206, s[12:15], s64 offen nt
	buffer_load_dwordx4 v[94:97], v206, s[12:15], s6 offen nt
	buffer_load_dwordx4 v[158:161], v206, s[12:15], s22 offen nt
	v_readlane_b32 s6, v245, 34
	s_nop 4
	buffer_load_dwordx4 v[34:37], v206, s[12:15], s6 offen nt
	buffer_load_dwordx4 v[30:33], v206, s[12:15], s23 offen nt
	buffer_load_dwordx4 v[22:25], v206, s[12:15], s60 offen nt
	buffer_load_dwordx4 v[18:21], v206, s[12:15], s61 offen nt
	buffer_load_dwordx4 v[26:29], v206, s[12:15], s56 offen nt
	buffer_load_dwordx4 v[106:109], v206, s[12:15], s57 offen nt
	buffer_load_dwordx4 v[102:105], v206, s[12:15], s18 offen nt
	buffer_load_dwordx4 v[98:101], v206, s[12:15], s19 offen nt
	s_waitcnt vmcnt(20)
	v_mov_b64_e32 v[52:53], v[4:5]
	v_mov_b64_e32 v[50:51], v[2:3]
	v_mov_b64_e32 v[54:55], v[62:63]
	v_mov_b64_e32 v[56:57], v[64:65]
	s_waitcnt vmcnt(18)
	v_mov_b64_e32 v[58:59], v[134:135]
	v_mov_b64_e32 v[60:61], v[136:137]
	s_waitcnt vmcnt(16)
	v_mov_b64_e32 v[144:145], v[140:141]
	v_mov_b64_e32 v[142:143], v[138:139]
	s_waitcnt vmcnt(14)
	v_mov_b64_e32 v[146:147], v[162:163]
	s_waitcnt vmcnt(7)
	v_mov_b64_e32 v[44:45], v[36:37]
	s_waitcnt vmcnt(6)
	v_mov_b64_e32 v[40:41], v[32:33]
	s_waitcnt vmcnt(5)
	v_mov_b64_e32 v[132:133], v[24:25]
	s_waitcnt vmcnt(4)
	v_mov_b64_e32 v[128:129], v[20:21]
	s_waitcnt vmcnt(3)
	v_mov_b64_e32 v[120:121], v[28:29]
	s_waitcnt vmcnt(2)
	v_mov_b64_e32 v[116:117], v[108:109]
	s_waitcnt vmcnt(1)
	v_mov_b64_e32 v[112:113], v[104:105]
	s_waitcnt vmcnt(0)
	v_mov_b64_e32 v[124:125], v[100:101]
	v_mov_b64_e32 v[150:151], v[166:167]
	v_mov_b64_e32 v[154:155], v[170:171]
	v_mov_b64_e32 v[46:47], v[158:159]
	v_mov_b64_e32 v[114:115], v[106:107]
	v_mov_b64_e32 v[118:119], v[26:27]
	v_mov_b64_e32 v[110:111], v[102:103]
	v_mov_b64_e32 v[122:123], v[98:99]
	v_mov_b64_e32 v[126:127], v[18:19]
	v_mov_b64_e32 v[130:131], v[22:23]
	v_mov_b64_e32 v[38:39], v[30:31]
	v_mov_b64_e32 v[42:43], v[34:35]
	v_mov_b64_e32 v[148:149], v[164:165]
	v_mov_b64_e32 v[152:153], v[168:169]
	v_mov_b64_e32 v[156:157], v[172:173]
	v_mov_b64_e32 v[48:49], v[160:161]
	s_cbranch_vccnz .LBB0_646
	v_readlane_b32 s6, v245, 37
	s_nop 4
	buffer_load_dwordx4 v[50:53], v206, s[12:15], s6 offen nt
	v_readlane_b32 s6, v245, 42
	s_nop 4
	buffer_load_dwordx4 v[54:57], v206, s[12:15], s6 offen nt
	v_readlane_b32 s6, v245, 43
	s_nop 4
	buffer_load_dwordx4 v[58:61], v206, s[12:15], s6 offen nt
	v_readlane_b32 s6, v245, 44
	s_nop 4
	buffer_load_dwordx4 v[142:145], v206, s[12:15], s6 offen nt
	v_readlane_b32 s6, v245, 45
	s_nop 4
	buffer_load_dwordx4 v[146:149], v206, s[12:15], s6 offen nt
	v_readlane_b32 s6, v245, 46
	s_nop 4
	buffer_load_dwordx4 v[150:153], v206, s[12:15], s6 offen nt
	v_readlane_b32 s6, v245, 47
	s_nop 4
	buffer_load_dwordx4 v[154:157], v206, s[12:15], s6 offen nt
	v_readlane_b32 s6, v245, 48
	s_nop 4
	buffer_load_dwordx4 v[46:49], v206, s[12:15], s6 offen nt
	v_readlane_b32 s6, v245, 49
	s_nop 4
	buffer_load_dwordx4 v[42:45], v206, s[12:15], s6 offen nt
	v_readlane_b32 s6, v245, 50
	s_nop 4
	buffer_load_dwordx4 v[38:41], v206, s[12:15], s6 offen nt
	v_readlane_b32 s6, v245, 51
	s_nop 4
	buffer_load_dwordx4 v[130:133], v206, s[12:15], s6 offen nt
	v_readlane_b32 s6, v245, 52
	s_nop 4
	buffer_load_dwordx4 v[126:129], v206, s[12:15], s6 offen nt
	v_readlane_b32 s6, v245, 53
	s_nop 4
	buffer_load_dwordx4 v[118:121], v206, s[12:15], s6 offen nt
	v_readlane_b32 s6, v245, 54
	s_nop 4
	buffer_load_dwordx4 v[114:117], v206, s[12:15], s6 offen nt
	v_readlane_b32 s6, v245, 55
	s_nop 4
	buffer_load_dwordx4 v[110:113], v206, s[12:15], s6 offen nt
	v_readlane_b32 s6, v245, 56
	s_nop 4
	buffer_load_dwordx4 v[122:125], v206, s[12:15], s6 offen nt

.LBB0_673:
	s_lshl_b32 s34, s9, 6
	s_ashr_i32 s9, s8, 31
	s_lshl_b64 s[8:9], s[8:9], 2
	v_or_b32_e32 v70, s34, v66
	s_add_u32 s2, s2, s8
	s_addc_u32 s3, s3, s9
	v_ashrrev_i32_e32 v71, 31, v70
	v_or_b32_e32 v6, 4, v70
	v_lshl_add_u64 v[2:3], s[2:3], 0, v[0:1]
	v_mul_lo_u32 v8, v71, s19
	v_mad_u64_u32 v[4:5], s[2:3], v70, s19, 0
	v_mad_u64_u32 v[6:7], s[2:3], v6, s19, 0
	v_add_u32_e32 v5, v5, v8
	v_add_u32_e32 v7, v7, v8
	v_lshl_add_u64 v[4:5], v[4:5], 2, v[2:3]
	v_lshl_add_u64 v[6:7], v[6:7], 2, v[2:3]
	global_load_dwordx4 v[62:65], v[4:5], off nt
	global_load_dwordx4 v[58:61], v[6:7], off nt
	v_or_b32_e32 v4, 8, v70
	v_or_b32_e32 v6, 12, v70
	v_mad_u64_u32 v[4:5], s[2:3], v4, s19, 0
	v_mad_u64_u32 v[6:7], s[2:3], v6, s19, 0
	v_add_u32_e32 v5, v5, v8
	v_add_u32_e32 v7, v7, v8
	v_lshl_add_u64 v[4:5], v[4:5], 2, v[2:3]
	v_lshl_add_u64 v[6:7], v[6:7], 2, v[2:3]
	global_load_dwordx4 v[54:57], v[4:5], off nt
	global_load_dwordx4 v[50:53], v[6:7], off nt
	v_or_b32_e32 v4, 16, v70
	v_or_b32_e32 v6, 20, v70
	v_mad_u64_u32 v[4:5], s[2:3], v4, s19, 0
	v_mad_u64_u32 v[6:7], s[2:3], v6, s19, 0
	v_add_u32_e32 v5, v5, v8
	v_add_u32_e32 v7, v7, v8
	v_lshl_add_u64 v[4:5], v[4:5], 2, v[2:3]
	v_lshl_add_u64 v[6:7], v[6:7], 2, v[2:3]
	global_load_dwordx4 v[46:49], v[4:5], off nt
	global_load_dwordx4 v[42:45], v[6:7], off nt
	v_or_b32_e32 v4, 24, v70
	v_or_b32_e32 v6, 28, v70
	v_mad_u64_u32 v[4:5], s[2:3], v4, s19, 0
	v_mad_u64_u32 v[6:7], s[2:3], v6, s19, 0
	v_add_u32_e32 v5, v5, v8
	v_add_u32_e32 v7, v7, v8
	v_lshl_add_u64 v[4:5], v[4:5], 2, v[2:3]
	v_lshl_add_u64 v[6:7], v[6:7], 2, v[2:3]
	global_load_dwordx4 v[38:41], v[4:5], off nt
	global_load_dwordx4 v[34:37], v[6:7], off nt
	v_or_b32_e32 v4, 32, v70
	v_or_b32_e32 v6, 36, v70
	v_mad_u64_u32 v[4:5], s[2:3], v4, s19, 0
	v_mad_u64_u32 v[6:7], s[2:3], v6, s19, 0
	v_add_u32_e32 v5, v5, v8
	v_add_u32_e32 v7, v7, v8
	v_lshl_add_u64 v[4:5], v[4:5], 2, v[2:3]
	v_lshl_add_u64 v[6:7], v[6:7], 2, v[2:3]
	global_load_dwordx4 v[30:33], v[4:5], off nt
	global_load_dwordx4 v[26:29], v[6:7], off nt
	v_or_b32_e32 v4, 40, v70
	v_or_b32_e32 v6, 44, v70
	v_mad_u64_u32 v[4:5], s[2:3], v4, s19, 0
	v_mad_u64_u32 v[6:7], s[2:3], v6, s19, 0
	v_add_u32_e32 v5, v5, v8
	v_add_u32_e32 v7, v7, v8
	v_lshl_add_u64 v[4:5], v[4:5], 2, v[2:3]
	v_lshl_add_u64 v[6:7], v[6:7], 2, v[2:3]
	global_load_dwordx4 v[22:25], v[4:5], off nt
	global_load_dwordx4 v[18:21], v[6:7], off nt
	v_or_b32_e32 v4, 48, v70
	v_or_b32_e32 v6, 52, v70
	v_mad_u64_u32 v[4:5], s[2:3], v4, s19, 0
	v_mad_u64_u32 v[6:7], s[2:3], v6, s19, 0
	v_add_u32_e32 v5, v5, v8
	v_add_u32_e32 v7, v7, v8
	v_lshl_add_u64 v[4:5], v[4:5], 2, v[2:3]
	v_lshl_add_u64 v[6:7], v[6:7], 2, v[2:3]
	global_load_dwordx4 v[14:17], v[4:5], off nt
	global_load_dwordx4 v[10:13], v[6:7], off nt
	v_or_b32_e32 v4, 56, v70
	v_or_b32_e32 v6, 60, v70
	v_mad_u64_u32 v[4:5], s[2:3], v4, s19, 0
	v_mad_u64_u32 v[6:7], s[2:3], v6, s19, 0
	v_add_u32_e32 v5, v5, v8
	v_add_u32_e32 v7, v7, v8
	v_lshl_add_u64 v[4:5], v[4:5], 2, v[2:3]
	v_lshl_add_u64 v[2:3], v[6:7], 2, v[2:3]
	global_load_dwordx4 v[6:9], v[4:5], off nt
	s_nop 0
	global_load_dwordx4 v[2:5], v[2:3], off nt
	s_cmp_lg_u64 s[6:7], 0
	s_cselect_b64 s[8:9], -1, 0
	s_cmp_eq_u64 s[6:7], 0
	s_cbranch_scc1 .LBB0_696
	v_lshl_add_u64 v[70:71], v[70:71], 2, s[6:7]
	global_load_dword v88, v[70:71], off
	global_load_dword v89, v[70:71], off offset:16
	global_load_dword v90, v[70:71], off offset:32
	global_load_dword v91, v[70:71], off offset:48
	global_load_dword v92, v[70:71], off offset:64
	global_load_dword v93, v[70:71], off offset:80
	global_load_dword v94, v[70:71], off offset:96
	global_load_dword v95, v[70:71], off offset:112
	global_load_dword v96, v[70:71], off offset:128
	global_load_dword v97, v[70:71], off offset:144
	global_load_dword v98, v[70:71], off offset:160
	global_load_dword v99, v[70:71], off offset:176
	global_load_dword v100, v[70:71], off offset:192
	global_load_dword v101, v[70:71], off offset:208
	global_load_dword v102, v[70:71], off offset:224
	global_load_dword v103, v[70:71], off offset:240
	s_ashr_i32 s35, s34, 31
	s_waitcnt vmcnt(0)
	v_mov_b32_e32 v70, v88
	v_pk_mul_f32 v[86:87], v[62:63], v[70:71] op_sel_hi:[1,0]
	v_pk_mul_f32 v[70:71], v[64:65], v[70:71] op_sel_hi:[1,0]
	ds_write2_b32 v83, v70, v71 offset0:2 offset1:3
	v_lshl_add_u64 v[70:71], s[34:35], 0, v[66:67]
	v_lshl_add_u64 v[70:71], v[70:71], 2, s[6:7]
	v_mov_b32_e32 v70, v89
	ds_write2_b32 v83, v86, v87 offset1:1
	s_cbranch_execnz .LBB0_676

.LBB0_676:
	s_waitcnt vmcnt(0)
	v_pk_mul_f32 v[58:59], v[58:59], v[70:71] op_sel_hi:[1,0]
	ds_write2_b32 v81, v58, v59 offset1:1
	v_pk_mul_f32 v[58:59], v[60:61], v[70:71] op_sel_hi:[1,0]
	v_cndmask_b32_e64 v60, 0, 1, s[8:9]
	v_cmp_ne_u32_e64 s[2:3], 1, v60
	s_andn2_b64 vcc, exec, s[8:9]
	ds_write2_b32 v81, v58, v59 offset0:2 offset1:3
	s_cbranch_vccnz .LBB0_697
	s_ashr_i32 s35, s34, 31
	v_lshl_add_u64 v[58:59], s[34:35], 0, v[66:67]
	v_lshl_add_u64 v[58:59], v[58:59], 2, s[6:7]
	v_mov_b32_e32 v60, v90
	s_nop 0
	v_mov_b32_e32 v58, v91
	s_waitcnt vmcnt(1)
	v_pk_mul_f32 v[62:63], v[54:55], v[60:61] op_sel_hi:[1,0]
	v_pk_mul_f32 v[60:61], v[56:57], v[60:61] op_sel_hi:[1,0]
	ds_write2_b32 v84, v62, v63 offset1:1
	ds_write2_b32 v84, v60, v61 offset0:2 offset1:3
	s_cbranch_execnz .LBB0_679

.LBB0_679:
	s_waitcnt vmcnt(0)
	v_pk_mul_f32 v[50:51], v[50:51], v[58:59] op_sel_hi:[1,0]
	ds_write2_b32 v82, v50, v51 offset1:1
	v_pk_mul_f32 v[50:51], v[52:53], v[58:59] op_sel_hi:[1,0]
	s_and_b64 vcc, exec, s[2:3]
	ds_write2_b32 v82, v50, v51 offset0:2 offset1:3
	s_cbranch_vccnz .LBB0_698
	s_ashr_i32 s35, s34, 31
	v_lshl_add_u64 v[50:51], s[34:35], 0, v[66:67]
	v_lshl_add_u64 v[50:51], v[50:51], 2, s[6:7]
	v_mov_b32_e32 v52, v92
	s_nop 0
	v_mov_b32_e32 v50, v93
	s_waitcnt vmcnt(1)
	v_pk_mul_f32 v[54:55], v[46:47], v[52:53] op_sel_hi:[1,0]
	v_pk_mul_f32 v[52:53], v[48:49], v[52:53] op_sel_hi:[1,0]
	ds_write2_b32 v85, v54, v55 offset1:1
	ds_write2_b32 v85, v52, v53 offset0:2 offset1:3
	s_cbranch_execnz .LBB0_682

.LBB0_682:
	s_waitcnt vmcnt(0)
	v_pk_mul_f32 v[42:43], v[42:43], v[50:51] op_sel_hi:[1,0]
	v_add_u32_e32 v46, 0x410, v85
	ds_write2_b32 v46, v42, v43 offset1:1
	v_pk_mul_f32 v[42:43], v[44:45], v[50:51] op_sel_hi:[1,0]
	v_add_u32_e32 v44, 0x418, v85
	ds_write2_b32 v44, v42, v43 offset1:1
	s_and_b64 vcc, exec, s[2:3]
	v_add_u32_e32 v43, 0x820, v85
	v_add_u32_e32 v44, 0x828, v85
	s_cbranch_vccnz .LBB0_699
	s_ashr_i32 s35, s34, 31
	v_lshl_add_u64 v[46:47], s[34:35], 0, v[66:67]
	v_lshl_add_u64 v[46:47], v[46:47], 2, s[6:7]
	v_mov_b32_e32 v42, v94
	s_waitcnt vmcnt(0)
	v_pk_mul_f32 v[48:49], v[38:39], v[42:43] op_sel_hi:[1,0]
	ds_write2_b32 v43, v48, v49 offset1:1
	v_pk_mul_f32 v[48:49], v[40:41], v[42:43] op_sel_hi:[1,0]
	v_mov_b32_e32 v42, v95
	ds_write2_b32 v44, v48, v49 offset1:1
	s_cbranch_execnz .LBB0_685

.LBB0_685:
	s_waitcnt vmcnt(0)
	v_pk_mul_f32 v[34:35], v[34:35], v[42:43] op_sel_hi:[1,0]
	v_add_u32_e32 v38, 0xc30, v85
	ds_write2_b32 v38, v34, v35 offset1:1
	v_pk_mul_f32 v[34:35], v[36:37], v[42:43] op_sel_hi:[1,0]
	v_add_u32_e32 v36, 0xc38, v85
	ds_write2_b32 v36, v34, v35 offset1:1
	s_and_b64 vcc, exec, s[2:3]
	v_add_u32_e32 v35, 0x1040, v85
	v_add_u32_e32 v36, 0x1048, v85
	s_cbranch_vccnz .LBB0_700
	s_ashr_i32 s35, s34, 31
	v_lshl_add_u64 v[38:39], s[34:35], 0, v[66:67]
	v_lshl_add_u64 v[38:39], v[38:39], 2, s[6:7]
	v_mov_b32_e32 v34, v96
	s_waitcnt vmcnt(0)
	v_pk_mul_f32 v[40:41], v[30:31], v[34:35] op_sel_hi:[1,0]
	ds_write2_b32 v35, v40, v41 offset1:1
	v_pk_mul_f32 v[40:41], v[32:33], v[34:35] op_sel_hi:[1,0]
	v_mov_b32_e32 v34, v97
	ds_write2_b32 v36, v40, v41 offset1:1
	s_cbranch_execnz .LBB0_688

.LBB0_688:
	s_waitcnt vmcnt(0)
	v_pk_mul_f32 v[26:27], v[26:27], v[34:35] op_sel_hi:[1,0]
	v_add_u32_e32 v30, 0x1450, v85
	ds_write2_b32 v30, v26, v27 offset1:1
	v_pk_mul_f32 v[26:27], v[28:29], v[34:35] op_sel_hi:[1,0]
	v_add_u32_e32 v28, 0x1458, v85
	ds_write2_b32 v28, v26, v27 offset1:1
	s_and_b64 vcc, exec, s[2:3]
	v_add_u32_e32 v27, 0x1860, v85
	v_add_u32_e32 v28, 0x1868, v85
	s_cbranch_vccnz .LBB0_701
	s_ashr_i32 s35, s34, 31
	v_lshl_add_u64 v[30:31], s[34:35], 0, v[66:67]
	v_lshl_add_u64 v[30:31], v[30:31], 2, s[6:7]
	v_mov_b32_e32 v26, v98
	s_waitcnt vmcnt(0)
	v_pk_mul_f32 v[32:33], v[22:23], v[26:27] op_sel_hi:[1,0]
	ds_write2_b32 v27, v32, v33 offset1:1
	v_pk_mul_f32 v[32:33], v[24:25], v[26:27] op_sel_hi:[1,0]
	v_mov_b32_e32 v26, v99
	ds_write2_b32 v28, v32, v33 offset1:1
	s_cbranch_execnz .LBB0_691

.LBB0_691:
	s_waitcnt vmcnt(0)
	v_pk_mul_f32 v[18:19], v[18:19], v[26:27] op_sel_hi:[1,0]
	v_add_u32_e32 v22, 0x1c70, v85
	ds_write2_b32 v22, v18, v19 offset1:1
	v_pk_mul_f32 v[18:19], v[20:21], v[26:27] op_sel_hi:[1,0]
	v_add_u32_e32 v20, 0x1c78, v85
	ds_write2_b32 v20, v18, v19 offset1:1
	s_and_b64 vcc, exec, s[2:3]
	v_add_u32_e32 v19, 0x2080, v85
	v_add_u32_e32 v20, 0x2088, v85
	s_cbranch_vccnz .LBB0_702
	s_ashr_i32 s35, s34, 31
	v_lshl_add_u64 v[22:23], s[34:35], 0, v[66:67]
	v_lshl_add_u64 v[22:23], v[22:23], 2, s[6:7]
	v_mov_b32_e32 v18, v100
	s_waitcnt vmcnt(0)
	v_pk_mul_f32 v[24:25], v[14:15], v[18:19] op_sel_hi:[1,0]
	ds_write2_b32 v19, v24, v25 offset1:1
	v_pk_mul_f32 v[24:25], v[16:17], v[18:19] op_sel_hi:[1,0]
	v_mov_b32_e32 v18, v101
	ds_write2_b32 v20, v24, v25 offset1:1
	s_cbranch_execnz .LBB0_694

.LBB0_694:
	s_waitcnt vmcnt(0)
	v_pk_mul_f32 v[10:11], v[10:11], v[18:19] op_sel_hi:[1,0]
	v_add_u32_e32 v14, 0x2490, v85
	ds_write2_b32 v14, v10, v11 offset1:1
	v_pk_mul_f32 v[10:11], v[12:13], v[18:19] op_sel_hi:[1,0]
	v_add_u32_e32 v12, 0x2498, v85
	ds_write2_b32 v12, v10, v11 offset1:1
	s_and_b64 vcc, exec, s[2:3]
	v_add_u32_e32 v11, 0x28a0, v85
	v_add_u32_e32 v12, 0x28a8, v85
	s_cbranch_vccnz .LBB0_703
	s_ashr_i32 s35, s34, 31
	v_lshl_add_u64 v[14:15], s[34:35], 0, v[66:67]
	v_lshl_add_u64 v[14:15], v[14:15], 2, s[6:7]
	v_mov_b32_e32 v10, v102
	s_waitcnt vmcnt(0)
	v_pk_mul_f32 v[16:17], v[6:7], v[10:11] op_sel_hi:[1,0]
	ds_write2_b32 v11, v16, v17 offset1:1
	v_pk_mul_f32 v[16:17], v[8:9], v[10:11] op_sel_hi:[1,0]
	v_mov_b32_e32 v10, v103
	ds_write2_b32 v12, v16, v17 offset1:1
	s_cbranch_execnz .LBB0_652
	s_branch .LBB0_651
